# combine-only queue fill (transposes in phase 0) + acquire once per workgroup + HGRN LDS prefetch + attention epilogue de-serialised
# baseline (speedup 1.0000x reference)
; DI void phase_mixer(const Params& p) {
;     ...
;   for (;;) {
;     __syncthreads();
;     if (threadIdx.x == 0) *sItem = (int)atomicAdd(ctr, 1u);
;     __syncthreads();
;     const int it = *sItem;
;     if (it >= 48 + 2048) break;
;     if (it < 48) hgrn_item(p, it); else attn_item(p, it - 48);
.Lcq_dispatch:
	s_cmpk_gt_i32 s12, 2607
	s_cbranch_scc1 .LBB0_953
	s_and_saveexec_b64 s[0:1], s[84:85]
	s_cbranch_execz .Lcq_go
	s_cmp_eq_u32 s32, 1
	s_cbranch_scc1 .Lcq_go
	s_mov_b32 s32, 1
	v_mov_b32_e32 v0, 0
